# NSA selected loop: SIMD-partner wave halves staggered (waves 4-7 run softmax/PV of pair i-1 then QK of pair i inside interval i) so MFMA of one wave overlaps VALU of its partner
# baseline (speedup 1.0000x reference)
; #define TIDX get_tid_()
; DI float bf2f(bf16_t b) { return __uint_as_float(((unsigned)b) << 16); }
; DI int crow(int i, int h) { return (i & 3) + 8 * (i >> 2) + 4 * h; }
; DI void nsa_main_item(const Params& p, int b, int head, int qb, const unsigned char* blut, const float* tbl) {
;   const int lane = TIDX & 63, r = lane & 31, h = lane >> 5;
;   const int g = head / 3, bg = b * 2 + g;
;   const int t = qb * 32 + r;
;   const float* tblh = tbl + head * 32;
;   bf16x8 qf[4];
;   load_q(qf, (const bf16_t*)(p.ws + OFF_QN) + (size_t)(b * 4096 + t) * 384 + head * 64 + 8 * h);
;   const unsigned long long selm = ((const unsigned long long*)(p.ws + OFF_SELM))[(size_t)bg * 4096 + t];
;   const float* gates = (const float*)(p.ws + OFF_GATES) + (size_t)(b * 4096 + t) * 18 + head * 3;
;   const float g1 = gates[1];
;   f32x16 y0, y1;
;   {
;     const bf16_t* oc = (const bf16_t*)(p.ws + OFF_OC) + (size_t)(b * 4096 + t) * 384 + head * 64;
;     const bf16_t* yw = (const bf16_t*)(p.ws + OFF_Y) + (size_t)(b * 4096 + t) * 768 + head * 64;
; #pragma unroll
;     for (int i = 0; i < 16; ++i) { y0[i] = bf2f(oc[crow(i, h)]) + bf2f(yw[crow(i, h)]); y1[i] = bf2f(oc[32 + crow(i, h)]) + bf2f(yw[32 + crow(i, h)]); }
;   }
;     ...
;   for (;;) {
;     const int item = wave_fetch(ctr);
;     if (item >= 128 * 48) break;
;     const int qb = 127 - item / 48, sub = item % 48;
;     nsa_main_item(p, sub / 6, sub % 6, qb, blut, tbl);
.LfY_skip:
	s_or_b64 exec, exec, s[8:9]
	s_barrier
	ds_read_b32 v0, v0
	v_lshrrev_b32_e32 v1, 6, v129
	s_waitcnt lgkmcnt(0)
	v_add_u32_e32 v0, v0, v1
	s_movk_i32 s8, 0x300
	s_waitcnt lgkmcnt(0)
	v_cmp_gt_i32_e32 vcc, s8, v0
	s_mov_b64 s[8:9], -1
	s_and_saveexec_b64 s[14:15], vcc
	s_cbranch_execz .LBB0_702
	v_lshrrev_b32_e32 v1, 4, v0
	v_lshlrev_b32_e32 v1, 3, v1
	v_and_b32_e32 v2, 7, v0
	v_add_u32_e32 v1, v1, v2
	v_bfe_u32 v2, v0, 3, 1
	v_mul_u32_u24_e32 v2, 3, v2
	v_add_u32_e32 v2, v2, v1
	v_mul_u32_u24_e32 v0, 0x5556, v1
	v_lshrrev_b32_e32 v0, 16, v0
	v_mul_u32_u24_e32 v0, 45, v0
	v_add3_u32 v0, v0, v2, s101
	s_mov_b32 s8, 0xd5555555
	v_mul_hi_i32 v1, v0, s8
	v_lshrrev_b32_e32 v2, 31, v1
	v_ashrrev_i32_e32 v1, 3, v1
	s_movk_i32 s8, 0x7f
	v_add3_u32 v217, v1, v2, s8
	s_mov_b32 s8, 0x2aaaaaab
	v_mul_hi_i32 v1, v0, s8
	v_lshrrev_b32_e32 v2, 31, v1
	v_lshrrev_b32_e32 v1, 3, v1
	v_add_u32_e32 v1, v1, v2
	v_mul_lo_u32 v1, v1, 48
	v_sub_u32_e32 v0, v0, v1
	v_mul_lo_u16_e32 v1, 43, v0
	v_lshrrev_b16_e32 v2, 15, v1
	v_add_u16_sdwa v1, v1, v2 dst_sel:DWORD dst_unused:UNUSED_PAD src0_sel:BYTE_1 src1_sel:DWORD
	v_bfe_i32 v2, v1, 0, 8
	v_mul_lo_u16_e32 v1, 6, v1
	v_sub_u16_e32 v0, v0, v1
	v_bfe_i32 v28, v0, 0, 8
	v_mov_b32_e32 v0, v129
	v_lshlrev_b32_e32 v31, 5, v217
	v_and_b32_e32 v29, 31, v0
	v_bfe_u32 v30, v0, 5, 1
	v_mul_lo_u16_e32 v0, 0x56, v28
	v_lshrrev_b16_e32 v1, 15, v0
	v_add_u16_sdwa v0, v0, v1 dst_sel:DWORD dst_unused:UNUSED_PAD src0_sel:BYTE_1 src1_sel:DWORD
	v_readlane_b32 s8, v253, 13
	v_bfe_i32 v0, v0, 0, 8
	v_or_b32_e32 v10, v29, v31
	v_readlane_b32 s9, v253, 14
	v_lshl_add_u32 v8, v2, 1, v0
	v_lshl_add_u32 v22, v2, 12, v10
	v_mov_b64_e32 v[0:1], s[8:9]
	s_movk_i32 s23, 0x300
	v_mad_i64_i32 v[0:1], s[8:9], v22, s23, v[0:1]
	v_lshlrev_b32_e32 v2, 6, v28
	v_ashrrev_i32_e32 v3, 31, v2
	v_readlane_b32 s8, v253, 23
	v_lshlrev_b64 v[2:3], 1, v[2:3]
	v_readlane_b32 s9, v253, 24
	v_lshl_add_u64 v[4:5], v[0:1], 0, v[2:3]
	v_lshlrev_b32_e32 v130, 3, v30
	v_mov_b64_e32 v[0:1], s[8:9]
	v_mad_i64_i32 v[0:1], s[8:9], v22, s23, v[0:1]
	v_readlane_b32 s8, v253, 19
	v_readlane_b32 s9, v253, 20
	v_lshl_add_u64 v[0:1], v[0:1], 0, v[2:3]
	v_ashrrev_i32_e32 v9, 31, v8
	v_mov_b64_e32 v[6:7], s[8:9]
	s_movk_i32 s8, 0x600
	v_mad_i64_i32 v[6:7], s[8:9], v22, s8, v[6:7]
	v_lshl_add_u64 v[2:3], v[6:7], 0, v[2:3]
	v_lshl_add_u64 v[12:13], v[0:1], 0, v[130:131]
	v_readlane_b32 s8, v253, 25
	v_lshlrev_b32_e32 v0, 3, v29
	v_lshl_add_u64 v[132:133], v[2:3], 0, v[130:131]
	v_lshlrev_b64 v[14:15], 19, v[8:9]
	v_readlane_b32 s9, v253, 26
	v_lshl_or_b32 v130, v30, 8, v0
	v_lshlrev_b32_e32 v20, 1, v130
	v_lshl_add_u64 v[16:17], s[8:9], 0, v[14:15]
	v_mov_b32_e32 v21, v131
	v_lshl_add_u64 v[148:149], v[16:17], 0, v[20:21]
	global_load_dwordx4 v[0:3], v[148:149], off
	v_lshlrev_b32_e32 v6, 4, v30
	v_mov_b32_e32 v7, v131
	v_lshl_add_u64 v[4:5], v[4:5], 0, v[6:7]
	global_load_dwordx4 v[80:83], v[4:5], off
	v_mov_b64_e32 v[6:7], s[34:35]
	s_movk_i32 s8, 0x48
	v_mad_i64_i32 v[6:7], s[8:9], v22, s8, v[6:7]
	v_mul_i32_i24_e32 v22, 3, v28
	v_ashrrev_i32_e32 v23, 31, v22
	v_cmp_eq_u32_e32 vcc, 0, v217
	v_lshl_add_u64 v[6:7], v[22:23], 2, v[6:7]
	s_mov_b32 s8, 0x165c4000
	v_cndmask_b32_e64 v18, v197, 0, vcc
	v_add_co_u32_e32 v22, vcc, s8, v6
	v_readlane_b32 s8, v253, 21
	s_nop 0
	v_addc_co_u32_e32 v23, vcc, 0, v7, vcc
	global_load_dwordx4 v[84:87], v[4:5], off offset:32
	global_load_dwordx4 v[88:91], v[4:5], off offset:64
	global_load_dwordx4 v[92:95], v[4:5], off offset:96
	global_load_dwordx2 v[136:137], v[12:13], off offset:64
	global_load_dwordx2 v[144:145], v[12:13], off offset:80
	global_load_dwordx2 v[150:151], v[12:13], off offset:32
	global_load_dwordx2 v[160:161], v[12:13], off offset:48
	global_load_dwordx2 v[134:135], v[132:133], off
	global_load_dwordx2 v[142:143], v[132:133], off offset:16
	global_load_dwordx2 v[152:153], v[132:133], off offset:32
	global_load_dwordx2 v[162:163], v[132:133], off offset:48
	global_load_dwordx2 v[154:155], v[12:13], off offset:96
	global_load_dwordx2 v[164:165], v[12:13], off offset:112
	global_load_dwordx4 v[4:7], v[148:149], off offset:1024
	global_load_dwordx2 v[138:139], v[132:133], off offset:64
	global_load_dwordx2 v[146:147], v[132:133], off offset:80
	global_load_dwordx2 v[158:159], v[132:133], off offset:96
	global_load_dwordx2 v[166:167], v[132:133], off offset:112
	v_lshlrev_b64 v[8:9], 15, v[8:9]
	v_readlane_b32 s9, v253, 22
	v_mov_b32_e32 v11, v131
	v_mov_b32_e32 v19, v131
	v_lshl_add_u64 v[8:9], s[8:9], 0, v[8:9]
	v_lshl_add_u64 v[24:25], v[10:11], 3, v[8:9]
	v_lshl_add_u64 v[26:27], v[16:17], 0, v[18:19]
	global_load_dwordx4 v[8:11], v[148:149], off offset:2048
	global_load_dwordx2 v[168:169], v[24:25], off
	global_load_dword v218, v[22:23], off offset:4
	global_load_dwordx2 v[140:141], v[12:13], off
	global_load_dwordx2 v[156:157], v[12:13], off offset:16
	global_load_dwordx4 v[16:19], v[148:149], off offset:3072
	v_readlane_b32 s8, v253, 27
	v_readlane_b32 s9, v253, 28
	v_lshl_add_u64 v[12:13], v[26:27], 0, v[20:21]
	global_load_dwordx4 v[108:111], v[12:13], off offset:3072
	global_load_dwordx4 v[104:107], v[12:13], off offset:2048
	global_load_dwordx4 v[100:103], v[12:13], off offset:1024
	global_load_dwordx4 v[96:99], v[12:13], off
	v_lshl_add_u64 v[14:15], s[8:9], 0, v[14:15]
	v_lshl_add_u64 v[170:171], v[14:15], 0, v[130:131]
	global_load_dwordx2 v[114:115], v[170:171], off offset:3584
	global_load_dwordx2 v[112:113], v[170:171], off offset:3072
	global_load_dwordx2 v[118:119], v[170:171], off offset:2560
	global_load_dwordx2 v[116:117], v[170:171], off offset:2048
	global_load_dwordx2 v[122:123], v[170:171], off offset:1536
	global_load_dwordx2 v[120:121], v[170:171], off offset:1024
	global_load_dwordx2 v[126:127], v[170:171], off offset:512
	global_load_dwordx2 v[124:125], v[170:171], off
	s_mov_b32 s56, 0
	s_mov_b32 s57, s56
	s_mov_b32 s58, s56
	s_mov_b32 s59, s56
	s_mov_b32 s60, s56
	s_mov_b32 s61, s56
	s_mov_b32 s62, s56
	s_mov_b32 s63, s56
	s_mov_b32 s64, s56
	s_mov_b32 s65, s56
	s_mov_b32 s66, s56
	s_mov_b32 s67, s56
	s_mov_b32 s68, s56
	s_mov_b32 s69, s56
	s_waitcnt vmcnt(36)
; #define MFMA32(a, b, c) __builtin_amdgcn_mfma_f32_32x32x16_bf16((a), (b), (c), 0, 0, 0)
; template <class KP, class VP, class ACT, class FILL>
; DI void attn_loop(AttnSt& st, const bf16x8 (&qf)[4], int k0, int k1, size_t vstride, KP kp, VP vp, ACT act, FILL fill) {
;   KVT cur, nxt;
;   {
;     KVT t0; load_kv(t0, kp(k0), vp(k0), vstride);
; #pragma unroll
;     for (int i = 0; i < 8; ++i) cur.v[i] = t0.v[i];
; #pragma unroll
;     for (int i = 0; i < 4; ++i) cur.k[i] = t0.k[i];
;   }
;   f32x16 s_cur;
;   { const float z = 0.f;
; #pragma unroll
;     for (int i = 0; i < 16; ++i) s_cur[i] = z; }
; #pragma unroll
;   for (int ss = 0; ss < 4; ++ss) s_cur = MFMA32(cur.k[ss], qf[ss], s_cur);
;   {
;     const int kn = (k0 < k1) ? k0 + 1 : k1;
;     const bf16_t* krow = kp(kn);
; #pragma unroll
;     for (int ss = 0; ss < 4; ++ss) nxt.k[ss] = *(const bf16x8*)(krow + 512 * ss);
;   }
; DI void nsa_main_item(const Params& p, int b, int head, int qb, const unsigned char* blut, const float* tbl) {
;     ...
;   {
;     const bf16_t* K = (const bf16_t*)(p.ws + OFF_KSEL) + (size_t)bg * 4096 * 64;
;     const bf16_t* Vt = (const bf16_t*)(p.ws + OFF_VSELT) + (size_t)bg * 64 * 4096;
;     AttnSt st; attn_init(st);
;     attn_loop(st, qf, 0, qb, 32,
;       [&](int kt) { return K + (size_t)kt * 2048 + (h * 32 + r) * 8; },
;       [&](int kt) { return Vt + (size_t)kt * 2048 + (h * 32 + r) * 4; },
	v_mfma_f32_32x32x16_bf16 v[48:63], v[0:3], v[80:83], 0
	s_mov_b32 s70, s56
	s_mov_b32 s71, s56
	v_lshlrev_b32_e32 v20, 2, v30
	v_lshl_add_u32 v219, v28, 7, 0
	v_subrev_u32_e32 v220, 31, v31
	v_sub_u32_e32 v221, v29, v20
	v_mov_b32_e32 v222, 0
	s_waitcnt vmcnt(22)
	v_mfma_f32_32x32x16_bf16 v[48:63], v[4:7], v[84:87], v[48:63]
	v_mov_b32_e32 v223, 0xff800000
	s_waitcnt vmcnt(17)
	v_mfma_f32_32x32x16_bf16 v[48:63], v[8:11], v[88:91], v[48:63]
	v_mov_b64_e32 v[0:1], s[56:57]
	v_mov_b64_e32 v[14:15], s[70:71]
	v_mov_b64_e32 v[2:3], s[58:59]
	v_mov_b64_e32 v[4:5], s[60:61]
	v_mov_b64_e32 v[6:7], s[62:63]
	v_mov_b64_e32 v[8:9], s[64:65]
	v_mov_b64_e32 v[10:11], s[66:67]
	s_waitcnt vmcnt(12)
	v_mfma_f32_32x32x16_bf16 v[48:63], v[16:19], v[92:95], v[48:63]
	v_mov_b64_e32 v[12:13], s[68:69]
	v_mov_b64_e32 v[30:31], v[14:15]
	s_mov_b64 s[58:59], 0
	v_mov_b64_e32 v[28:29], v[12:13]
	v_mov_b64_e32 v[26:27], v[10:11]
	v_mov_b64_e32 v[24:25], v[8:9]
	v_mov_b64_e32 v[22:23], v[6:7]
	v_mov_b64_e32 v[20:21], v[4:5]
	v_mov_b64_e32 v[18:19], v[2:3]
	v_mov_b64_e32 v[16:17], v[0:1]
	s_waitcnt vmcnt(0)
	v_readfirstlane_b32 s60, v217
	v_lshrrev_b32_e32 v246, 6, v129
	v_and_b32_e32 v247, 63, v129
	v_lshlrev_b32_e32 v247, 3, v247
	v_readfirstlane_b32 s58, v246
	v_mov_b32_e32 v224, s60
	v_mov_b32_e32 v225, 0x1940
	v_lshl_add_u32 v234, v246, 2, v225
	ds_write_b32 v234, v224
	s_waitcnt lgkmcnt(0)
	s_barrier
	ds_read_b128 v[226:229], v225
	ds_read_b128 v[230:233], v225 offset:16
	s_waitcnt lgkmcnt(0)
	v_max3_u32 v226, v226, v227, v228
	v_max3_u32 v226, v226, v229, v230
	v_max3_u32 v226, v226, v231, v232
	v_max_u32_e32 v226, v226, v233
	s_nop 0
	v_readfirstlane_b32 s59, v226
	s_mov_b32 s56, 0
	s_mov_b32 s23, 0
	s_mov_b32 s100, 0x10000
	s_lshr_b32 s24, s59, 1
	s_min_u32 s24, s23, s24
	s_lshl_b32 s26, s24, 13
	s_lshl_b32 s24, s58, 10
	s_add_u32 s26, s26, s24
	s_mov_b32 s27, 0
	v_lshl_add_u64 v[248:249], v[148:149], 0, s[26:27]
	v_lshl_add_u64 v[250:251], v[170:171], 0, s[26:27]
	v_add_co_u32_e32 v250, vcc, v250, v247
	v_addc_co_u32_e32 v251, vcc, 0, v251, vcc
	s_add_u32 s24, s24, s100
	s_mov_b32 m0, s24
	s_nop 0
	global_load_lds_dwordx4 v[248:249], off
	s_add_u32 s24, s24, 0x2000
	s_mov_b32 m0, s24
	s_nop 0
	global_load_lds_dwordx4 v[250:251], off
	s_mov_b32 s23, 1
	s_mov_b32 s100, 0x14000
	s_lshr_b32 s24, s59, 1
	s_min_u32 s24, s23, s24
	s_lshl_b32 s26, s24, 13
	s_lshl_b32 s24, s58, 10
	s_add_u32 s26, s26, s24
	s_mov_b32 s27, 0
	v_lshl_add_u64 v[248:249], v[148:149], 0, s[26:27]
	v_lshl_add_u64 v[250:251], v[170:171], 0, s[26:27]
	v_add_co_u32_e32 v250, vcc, v250, v247
	v_addc_co_u32_e32 v251, vcc, 0, v251, vcc
	s_add_u32 s24, s24, s100
	s_mov_b32 m0, s24
	s_nop 0
	global_load_lds_dwordx4 v[248:249], off
	s_add_u32 s24, s24, 0x2000
	s_mov_b32 m0, s24
	s_nop 0
	global_load_lds_dwordx4 v[250:251], off
	s_mov_b32 s100, 0x10000
	v_lshrrev_b32_e32 v246, 6, v129
	v_mul_u32_u24_e32 v246, 6912, v246
	v_add_u32_e32 v242, 8192, v246
	v_and_b32_e32 v246, 63, v129
	v_add_u32_e32 v224, -64, v246
	v_mov_b32_e32 v224, 0
	v_mov_b32_e32 v225, v246
	v_add_u32_e32 v226, 64, v246
	v_add_u32_e32 v227, 128, v246
	v_add_u32_e32 v228, 192, v246
	v_add_u32_e32 v229, 256, v246
	v_add_u32_e32 v230, 320, v246
	v_add_u32_e32 v231, 384, v246
	v_add_u32_e32 v232, 448, v246
	ds_read_u8 v224, v224
	ds_read_u8 v225, v225
	ds_read_u8 v226, v226
	ds_read_u8 v227, v227
	ds_read_u8 v228, v228
	ds_read_u8 v229, v229
	ds_read_u8 v230, v230
	ds_read_u8 v231, v231
	ds_read_u8 v232, v232
	s_waitcnt lgkmcnt(8)
	v_lshl_add_u32 v224, v224, 2, v219
	s_waitcnt lgkmcnt(7)
	v_lshl_add_u32 v225, v225, 2, v219
	s_waitcnt lgkmcnt(6)
	v_lshl_add_u32 v226, v226, 2, v219
	s_waitcnt lgkmcnt(5)
	v_lshl_add_u32 v227, v227, 2, v219
	s_waitcnt lgkmcnt(4)
	v_lshl_add_u32 v228, v228, 2, v219
	s_waitcnt lgkmcnt(3)
	v_lshl_add_u32 v229, v229, 2, v219
	s_waitcnt lgkmcnt(2)
	v_lshl_add_u32 v230, v230, 2, v219
	s_waitcnt lgkmcnt(1)
	v_lshl_add_u32 v231, v231, 2, v219
	s_waitcnt lgkmcnt(0)
	v_lshl_add_u32 v232, v232, 2, v219
	ds_read_b32 v224, v224 offset:4096
	ds_read_b32 v225, v225 offset:4096
	ds_read_b32 v226, v226 offset:4096
	ds_read_b32 v227, v227 offset:4096
	ds_read_b32 v228, v228 offset:4096
	ds_read_b32 v229, v229 offset:4096
	ds_read_b32 v230, v230 offset:4096
	ds_read_b32 v231, v231 offset:4096
	ds_read_b32 v232, v232 offset:4096
	v_lshl_add_u32 v244, v246, 2, v242
	s_waitcnt lgkmcnt(8)
	ds_write_b32 v244, v224 offset:0
	s_waitcnt lgkmcnt(7)
; DI void bias16(const unsigned char* blut, const float* tblh, const int (&dist)[16], float (&bv)[16]) {
;   int bk[16];
; #pragma unroll
;   for (int i = 0; i < 16; ++i) { const int d = dist[i] < 0 ? 0 : (dist[i] > 2048 ? 2048 : dist[i]); bk[i] = blut[d]; }
; #pragma unroll
;   for (int i = 0; i < 16; ++i) asm volatile("" : "+v"(bk[i]));
; #pragma unroll
;   for (int i = 0; i < 16; ++i) bv[i] = tblh[bk[i]];
; #pragma unroll
;   for (int i = 0; i < 16; ++i) asm volatile("" : "+v"(bv[i]));
; }
	ds_write_b32 v244, v225 offset:256
	s_waitcnt lgkmcnt(6)
	ds_write_b32 v244, v226 offset:512
	s_waitcnt lgkmcnt(5)
	ds_write_b32 v244, v227 offset:768
	s_waitcnt lgkmcnt(4)
	ds_write_b32 v244, v228 offset:1024
	s_waitcnt lgkmcnt(3)
	ds_write_b32 v244, v229 offset:1280
	s_waitcnt lgkmcnt(2)
	ds_write_b32 v244, v230 offset:1536
	s_waitcnt lgkmcnt(1)
	ds_write_b32 v244, v231 offset:1792
	s_waitcnt lgkmcnt(0)
	ds_write_b32 v244, v232 offset:2048
	v_add_u32_e32 v224, 512, v246
	v_add_u32_e32 v225, 576, v246
	v_add_u32_e32 v226, 640, v246
	v_add_u32_e32 v227, 704, v246
	v_add_u32_e32 v228, 768, v246
	v_add_u32_e32 v229, 832, v246
	v_add_u32_e32 v230, 896, v246
	v_add_u32_e32 v231, 960, v246
	v_add_u32_e32 v232, 1024, v246
	ds_read_u8 v224, v224
	ds_read_u8 v225, v225
	ds_read_u8 v226, v226
	ds_read_u8 v227, v227
	ds_read_u8 v228, v228
	ds_read_u8 v229, v229
	ds_read_u8 v230, v230
	ds_read_u8 v231, v231
	ds_read_u8 v232, v232
	s_waitcnt lgkmcnt(8)
	v_lshl_add_u32 v224, v224, 2, v219
	s_waitcnt lgkmcnt(7)
	v_lshl_add_u32 v225, v225, 2, v219
	s_waitcnt lgkmcnt(6)
	v_lshl_add_u32 v226, v226, 2, v219
	s_waitcnt lgkmcnt(5)
	v_lshl_add_u32 v227, v227, 2, v219
	s_waitcnt lgkmcnt(4)
	v_lshl_add_u32 v228, v228, 2, v219
	s_waitcnt lgkmcnt(3)
	v_lshl_add_u32 v229, v229, 2, v219
	s_waitcnt lgkmcnt(2)
	v_lshl_add_u32 v230, v230, 2, v219
	s_waitcnt lgkmcnt(1)
	v_lshl_add_u32 v231, v231, 2, v219
	s_waitcnt lgkmcnt(0)
	v_lshl_add_u32 v232, v232, 2, v219
	ds_read_b32 v224, v224 offset:4096
	ds_read_b32 v225, v225 offset:4096
	ds_read_b32 v226, v226 offset:4096
	ds_read_b32 v227, v227 offset:4096
	ds_read_b32 v228, v228 offset:4096
	ds_read_b32 v229, v229 offset:4096
	ds_read_b32 v230, v230 offset:4096
	ds_read_b32 v231, v231 offset:4096
	ds_read_b32 v232, v232 offset:4096
	v_lshl_add_u32 v244, v246, 2, v242
	s_waitcnt lgkmcnt(8)
	ds_write_b32 v244, v224 offset:2304
	s_waitcnt lgkmcnt(7)
	ds_write_b32 v244, v225 offset:2560
	s_waitcnt lgkmcnt(6)
	ds_write_b32 v244, v226 offset:2816
	s_waitcnt lgkmcnt(5)
	ds_write_b32 v244, v227 offset:3072
	s_waitcnt lgkmcnt(4)
	ds_write_b32 v244, v228 offset:3328
	s_waitcnt lgkmcnt(3)
	ds_write_b32 v244, v229 offset:3584
	s_waitcnt lgkmcnt(2)
	ds_write_b32 v244, v230 offset:3840
	s_waitcnt lgkmcnt(1)
	ds_write_b32 v244, v231 offset:4096
	s_waitcnt lgkmcnt(0)
	ds_write_b32 v244, v232 offset:4352
	v_add_u32_e32 v224, 1088, v246
	v_add_u32_e32 v225, 1152, v246
	v_add_u32_e32 v226, 1216, v246
	v_add_u32_e32 v227, 1280, v246
	v_add_u32_e32 v228, 1344, v246
	v_add_u32_e32 v229, 1408, v246
	v_add_u32_e32 v230, 1472, v246
	v_add_u32_e32 v231, 1536, v246
	v_add_u32_e32 v232, 1600, v246
	ds_read_u8 v224, v224
	ds_read_u8 v225, v225
	ds_read_u8 v226, v226
	ds_read_u8 v227, v227
	ds_read_u8 v228, v228
	ds_read_u8 v229, v229
	ds_read_u8 v230, v230
	ds_read_u8 v231, v231
	ds_read_u8 v232, v232
	s_waitcnt lgkmcnt(8)
	v_lshl_add_u32 v224, v224, 2, v219
	s_waitcnt lgkmcnt(7)
	v_lshl_add_u32 v225, v225, 2, v219
	s_waitcnt lgkmcnt(6)
	v_lshl_add_u32 v226, v226, 2, v219
	s_waitcnt lgkmcnt(5)
	v_lshl_add_u32 v227, v227, 2, v219
	s_waitcnt lgkmcnt(4)
	v_lshl_add_u32 v228, v228, 2, v219
	s_waitcnt lgkmcnt(3)
	v_lshl_add_u32 v229, v229, 2, v219
	s_waitcnt lgkmcnt(2)
	v_lshl_add_u32 v230, v230, 2, v219
	s_waitcnt lgkmcnt(1)
	v_lshl_add_u32 v231, v231, 2, v219
	s_waitcnt lgkmcnt(0)
	v_lshl_add_u32 v232, v232, 2, v219
	ds_read_b32 v224, v224 offset:4096
	ds_read_b32 v225, v225 offset:4096
	ds_read_b32 v226, v226 offset:4096
	ds_read_b32 v227, v227 offset:4096
	ds_read_b32 v228, v228 offset:4096
	ds_read_b32 v229, v229 offset:4096
	ds_read_b32 v230, v230 offset:4096
	ds_read_b32 v231, v231 offset:4096
	ds_read_b32 v232, v232 offset:4096
	v_lshl_add_u32 v244, v246, 2, v242
	s_waitcnt lgkmcnt(8)
	ds_write_b32 v244, v224 offset:4608
	s_waitcnt lgkmcnt(7)
	ds_write_b32 v244, v225 offset:4864
	s_waitcnt lgkmcnt(6)
	ds_write_b32 v244, v226 offset:5120
	s_waitcnt lgkmcnt(5)
	ds_write_b32 v244, v227 offset:5376
	s_waitcnt lgkmcnt(4)
	ds_write_b32 v244, v228 offset:5632
	s_waitcnt lgkmcnt(3)
	ds_write_b32 v244, v229 offset:5888
	s_waitcnt lgkmcnt(2)
	ds_write_b32 v244, v230 offset:6144
	s_waitcnt lgkmcnt(1)
	ds_write_b32 v244, v231 offset:6400
	s_waitcnt lgkmcnt(0)
	ds_write_b32 v244, v232 offset:6656
	ds_read_b32 v240, v219 offset:4220
	v_add_u32_e32 v242, 148, v242
	v_mov_b32_e32 v243, 0x7f800000
	s_waitcnt lgkmcnt(0)
	s_cmp_ge_u32 s58, 4
	s_cbranch_scc1 .Lasel_loopB

; #define MFMA32(a, b, c) __builtin_amdgcn_mfma_f32_32x32x16_bf16((a), (b), (c), 0, 0, 0)
; #define NEGINF (-__builtin_inff())
; DI int crow(int i, int h) { return (i & 3) + 8 * (i >> 2) + 4 * h; }
; template <class KP, class VP, class ACT, class FILL>
; DI void attn_loop(AttnSt& st, const bf16x8 (&qf)[4], int k0, int k1, size_t vstride, KP kp, VP vp, ACT act, FILL fill) {
;     ...
;   for (int kt = k0; kt <= k1; ++kt) {
;     const int kn = (kt < k1) ? kt + 1 : k1;
;     const int kn2 = (kt + 2 <= k1) ? kt + 2 : k1;
;     {
;       const bf16_t* v0 = vp(kn);
; #pragma unroll
;       for (int j = 0; j < 8; ++j) nxt.v[j] = *(const s16x4*)(v0 + 256 * j);
;     }
;     bf16x8 k2[4];
;     {
;       const bf16_t* krow = kp(kn2);
; #pragma unroll
;       for (int ss = 0; ss < 4; ++ss) k2[ss] = *(const bf16x8*)(krow + 512 * ss);
;     }
;     f32x16 s_next;
; #pragma unroll
;     for (int i = 0; i < 16; ++i) s_next[i] = 0.f;
; #pragma unroll
;     for (int ss = 0; ss < 4; ++ss) s_next = MFMA32(nxt.k[ss], qf[ss], s_next);
;     if (act(kt)) {
;       float lg[16];
;       fill(kt, s_cur, lg);
;       softmax_step_r(st, lg, cur);
;     }
;     s_cur = s_next;
; #pragma unroll
;     for (int i = 0; i < 8; ++i) cur.v[i] = nxt.v[i];
; #pragma unroll
;     for (int ss = 0; ss < 4; ++ss) nxt.k[ss] = k2[ss];
;   }
; DI void nsa_main_item(const Params& p, int b, int head, int qb, const unsigned char* blut, const float* tbl) {
;     ...
;       [&](int kt, const f32x16& s, float (&lg)[16]) {
;         const bool bs = (selm >> (kt >> 1)) & 1ull;
;         if (qb * 32 - (kt * 32 + 31) >= 1513) {
;           const float b31 = tblh[31];
; #pragma unroll
;           for (int i = 0; i < 16; ++i) lg[i] = bs ? s[i] + b31 : NEGINF;
;         } else {
;           int dist[16]; float bv[16];
; #pragma unroll
;           for (int i = 0; i < 16; ++i) dist[i] = t - (kt * 32 + crow(i, h));
;           bias16(blut, tblh, dist, bv);
; #pragma unroll
;           for (int i = 0; i < 16; ++i) lg[i] = (bs && dist[i] >= 0) ? s[i] + bv[i] : NEGINF;
;         }
.Lasel_skip:
	s_add_u32 s100, s100, 0x4000
	s_cmp_eq_u32 s100, 0x1c000
	s_cselect_b32 s100, 0x10000, s100
	s_add_u32 s56, s56, 2
	s_cmp_le_u32 s56, s59
	s_cbranch_scc1 .Lasel_loop
	s_branch .Lasel_done
.Lasel_loopB:
	s_waitcnt vmcnt(2)
	s_barrier
	s_lshr_b32 s23, s56, 1
	s_add_u32 s23, s23, 2
	s_sub_u32 s61, s100, 0x4000
	s_cmp_lt_u32 s61, 0x10000
	s_cselect_b32 s61, 0x18000, s61
	s_lshr_b32 s24, s59, 1
	s_min_u32 s24, s23, s24
	s_lshl_b32 s26, s24, 13
	s_lshl_b32 s24, s58, 10
	s_add_u32 s26, s26, s24
	s_mov_b32 s27, 0
	v_lshl_add_u64 v[248:249], v[148:149], 0, s[26:27]
	v_lshl_add_u64 v[250:251], v[170:171], 0, s[26:27]
	v_add_co_u32_e32 v250, vcc, v250, v247
	v_addc_co_u32_e32 v251, vcc, 0, v251, vcc
	s_add_u32 s24, s24, s61
	s_mov_b32 m0, s24
	s_nop 0
	global_load_lds_dwordx4 v[248:249], off
	s_add_u32 s24, s24, 0x2000
	s_mov_b32 m0, s24
	s_nop 0
	global_load_lds_dwordx4 v[250:251], off
	s_cmp_lt_u32 s56, 2
	s_cbranch_scc1 .Lasel_skipB1
	s_sub_u32 s24, s56, 2
	s_cmp_le_u32 s24, s60
	s_cbranch_scc0 .Lasel_skipB1
	s_sub_i32 s61, s60, s24
	s_lshr_b32 s23, s24, 1
	v_lshrrev_b64 v[248:249], s23, v[168:169]
	v_and_b32_e32 v248, 1, v248
	v_cmp_eq_u32_e64 s[62:63], 1, v248
	s_cmp_ge_i32 s61, 50
	s_cbranch_scc1 .Lasel_farb
	s_lshl_b32 s23, s61, 5
	v_add_u32_e32 v241, s23, v221
	v_lshl_add_u32 v244, v241, 2, v242
	v_subrev_u32_e32 v245, 128, v244
	ds_read_b32 v224, v244 offset:108
	ds_read_b32 v225, v244 offset:104
	ds_read_b32 v226, v244 offset:100
	ds_read_b32 v227, v244 offset:96
	ds_read_b32 v228, v244 offset:76
	ds_read_b32 v229, v244 offset:72
	ds_read_b32 v230, v244 offset:68
	ds_read_b32 v231, v244 offset:64
	ds_read_b32 v232, v244 offset:44
	ds_read_b32 v233, v244 offset:40
	ds_read_b32 v234, v244 offset:36
	ds_read_b32 v235, v244 offset:32
	ds_read_b32 v236, v244 offset:12
	ds_read_b32 v237, v244 offset:8
	ds_read_b32 v238, v244 offset:4
	ds_read_b32 v239, v244 offset:0
	s_waitcnt lgkmcnt(8)
	v_add_f32_e32 v32, v32, v224
	v_add_f32_e32 v33, v33, v225
	v_add_f32_e32 v34, v34, v226
	v_add_f32_e32 v35, v35, v227
	v_add_f32_e32 v36, v36, v228
	v_add_f32_e32 v37, v37, v229
	v_add_f32_e32 v38, v38, v230
	v_add_f32_e32 v39, v39, v231
	s_waitcnt lgkmcnt(0)
	v_add_f32_e32 v40, v40, v232
	v_add_f32_e32 v41, v41, v233
	v_add_f32_e32 v42, v42, v234
	v_add_f32_e32 v43, v43, v235
	v_add_f32_e32 v44, v44, v236
	v_add_f32_e32 v45, v45, v237
	v_add_f32_e32 v46, v46, v238
	v_add_f32_e32 v47, v47, v239
	ds_read_b32 v224, v245 offset:108
	ds_read_b32 v225, v245 offset:104
	ds_read_b32 v226, v245 offset:100
	ds_read_b32 v227, v245 offset:96
	ds_read_b32 v228, v245 offset:76
	ds_read_b32 v229, v245 offset:72
	ds_read_b32 v230, v245 offset:68
	ds_read_b32 v231, v245 offset:64
	ds_read_b32 v232, v245 offset:44
	ds_read_b32 v233, v245 offset:40
	ds_read_b32 v234, v245 offset:36
	ds_read_b32 v235, v245 offset:32
	ds_read_b32 v236, v245 offset:12
	ds_read_b32 v237, v245 offset:8
	ds_read_b32 v238, v245 offset:4
	ds_read_b32 v239, v245 offset:0
	s_waitcnt lgkmcnt(8)
	v_add_f32_e32 v48, v48, v224
	v_add_f32_e32 v49, v49, v225
	v_add_f32_e32 v50, v50, v226
	v_add_f32_e32 v51, v51, v227
	v_add_f32_e32 v52, v52, v228
	v_add_f32_e32 v53, v53, v229
	v_add_f32_e32 v54, v54, v230
	v_add_f32_e32 v55, v55, v231
	s_waitcnt lgkmcnt(0)
	v_add_f32_e32 v56, v56, v232
	v_add_f32_e32 v57, v57, v233
	v_add_f32_e32 v58, v58, v234
	v_add_f32_e32 v59, v59, v235
	v_add_f32_e32 v60, v60, v236
	v_add_f32_e32 v61, v61, v237
	v_add_f32_e32 v62, v62, v238
	v_add_f32_e32 v63, v63, v239
	s_cmp_ge_i32 s61, 2
	s_cbranch_scc1 .Lasel_softmaxb
	v_subrev_u32_e32 v246, 32, v241
	v_cmp_le_i32_e32 vcc, 0, v241
	s_nop 1
	v_cndmask_b32_e32 v32, v199, v32, vcc
	v_cmp_le_i32_e32 vcc, 1, v241
	s_nop 1
	v_cndmask_b32_e32 v33, v199, v33, vcc
	v_cmp_le_i32_e32 vcc, 2, v241
	s_nop 1
	v_cndmask_b32_e32 v34, v199, v34, vcc
	v_cmp_le_i32_e32 vcc, 3, v241
	s_nop 1
	v_cndmask_b32_e32 v35, v199, v35, vcc
	v_cmp_le_i32_e32 vcc, 8, v241
	s_nop 1
	v_cndmask_b32_e32 v36, v199, v36, vcc
	v_cmp_le_i32_e32 vcc, 9, v241
	s_nop 1
	v_cndmask_b32_e32 v37, v199, v37, vcc
	v_cmp_le_i32_e32 vcc, 10, v241
	s_nop 1
	v_cndmask_b32_e32 v38, v199, v38, vcc
	v_cmp_le_i32_e32 vcc, 11, v241
	s_nop 1
	v_cndmask_b32_e32 v39, v199, v39, vcc
	v_cmp_le_i32_e32 vcc, 16, v241
	s_nop 1
	v_cndmask_b32_e32 v40, v199, v40, vcc
	v_cmp_le_i32_e32 vcc, 17, v241
	s_nop 1
	v_cndmask_b32_e32 v41, v199, v41, vcc
	v_cmp_le_i32_e32 vcc, 18, v241
	s_nop 1
	v_cndmask_b32_e32 v42, v199, v42, vcc
	v_cmp_le_i32_e32 vcc, 19, v241
	s_nop 1
	v_cndmask_b32_e32 v43, v199, v43, vcc
	v_cmp_le_i32_e32 vcc, 24, v241
	s_nop 1
	v_cndmask_b32_e32 v44, v199, v44, vcc
	v_cmp_le_i32_e32 vcc, 25, v241
	s_nop 1
	v_cndmask_b32_e32 v45, v199, v45, vcc
	v_cmp_le_i32_e32 vcc, 26, v241
	s_nop 1
	v_cndmask_b32_e32 v46, v199, v46, vcc
	v_cmp_le_i32_e32 vcc, 27, v241
	s_nop 1
	v_cndmask_b32_e32 v47, v199, v47, vcc
	v_cmp_le_i32_e32 vcc, 0, v246
	s_nop 1
	v_cndmask_b32_e32 v48, v199, v48, vcc
	v_cmp_le_i32_e32 vcc, 1, v246
	s_nop 1
	v_cndmask_b32_e32 v49, v199, v49, vcc
	v_cmp_le_i32_e32 vcc, 2, v246
	s_nop 1
	v_cndmask_b32_e32 v50, v199, v50, vcc
	v_cmp_le_i32_e32 vcc, 3, v246
	s_nop 1
	v_cndmask_b32_e32 v51, v199, v51, vcc
	v_cmp_le_i32_e32 vcc, 8, v246
	s_nop 1
	v_cndmask_b32_e32 v52, v199, v52, vcc
	v_cmp_le_i32_e32 vcc, 9, v246
	s_nop 1
	v_cndmask_b32_e32 v53, v199, v53, vcc
	v_cmp_le_i32_e32 vcc, 10, v246
	s_nop 1
	v_cndmask_b32_e32 v54, v199, v54, vcc
	v_cmp_le_i32_e32 vcc, 11, v246
	s_nop 1
	v_cndmask_b32_e32 v55, v199, v55, vcc
	v_cmp_le_i32_e32 vcc, 16, v246
	s_nop 1
	v_cndmask_b32_e32 v56, v199, v56, vcc
	v_cmp_le_i32_e32 vcc, 17, v246
	s_nop 1
	v_cndmask_b32_e32 v57, v199, v57, vcc
	v_cmp_le_i32_e32 vcc, 18, v246
	s_nop 1
	v_cndmask_b32_e32 v58, v199, v58, vcc
	v_cmp_le_i32_e32 vcc, 19, v246
	s_nop 1
	v_cndmask_b32_e32 v59, v199, v59, vcc
	v_cmp_le_i32_e32 vcc, 24, v246
	s_nop 1
	v_cndmask_b32_e32 v60, v199, v60, vcc
	v_cmp_le_i32_e32 vcc, 25, v246
	s_nop 1
	v_cndmask_b32_e32 v61, v199, v61, vcc
	v_cmp_le_i32_e32 vcc, 26, v246
	s_nop 1
	v_cndmask_b32_e32 v62, v199, v62, vcc
	v_cmp_le_i32_e32 vcc, 27, v246
	s_nop 1
	v_cndmask_b32_e32 v63, v199, v63, vcc
	s_branch .Lasel_softmaxb

; #define MFMA32(a, b, c) __builtin_amdgcn_mfma_f32_32x32x16_bf16((a), (b), (c), 0, 0, 0)
; DI void load_kv(KVT& t, const bf16_t* krow, const bf16_t* v0, size_t rowstride) {
; #pragma unroll
;   for (int ss = 0; ss < 4; ++ss) t.k[ss] = *(const bf16x8*)(krow + 512 * ss);
; #pragma unroll
;   for (int j = 0; j < 8; ++j) t.v[j] = *(const s16x4*)(v0 + 256 * j);
; }
; template <class KP, class VP, class ACT, class FILL>
; DI void attn_loop(AttnSt& st, const bf16x8 (&qf)[4], int k0, int k1, size_t vstride, KP kp, VP vp, ACT act, FILL fill) {
;     ...
;     {
;       const bf16_t* krow = kp(kn2);
; #pragma unroll
;       for (int ss = 0; ss < 4; ++ss) k2[ss] = *(const bf16x8*)(krow + 512 * ss);
;     }
;     f32x16 s_next;
; #pragma unroll
;     for (int i = 0; i < 16; ++i) s_next[i] = 0.f;
; #pragma unroll
;     for (int ss = 0; ss < 4; ++ss) s_next = MFMA32(nxt.k[ss], qf[ss], s_next);
.Lasel_skipB1:
	s_cmp_le_u32 s56, s60
	s_cbranch_scc0 .Lasel_skipB2
	v_lshl_add_u32 v248, v247, 1, s100
	ds_read_b128 v[96:99], v248 offset:0
	ds_read_b128 v[100:103], v248 offset:1024
	ds_read_b128 v[104:107], v248 offset:2048
	ds_read_b128 v[108:111], v248 offset:3072
	ds_read_b128 v[112:115], v248 offset:4096
	ds_read_b128 v[116:119], v248 offset:5120
	ds_read_b128 v[120:123], v248 offset:6144
	ds_read_b128 v[124:127], v248 offset:7168
	s_waitcnt lgkmcnt(0)
	v_mfma_f32_32x32x16_bf16 v[32:47], v[96:99], v[80:83], 0
	v_mfma_f32_32x32x16_bf16 v[48:63], v[112:115], v[80:83], 0
	v_mfma_f32_32x32x16_bf16 v[32:47], v[100:103], v[84:87], v[32:47]
	v_mfma_f32_32x32x16_bf16 v[48:63], v[116:119], v[84:87], v[48:63]
	v_mfma_f32_32x32x16_bf16 v[32:47], v[104:107], v[88:91], v[32:47]
	v_mfma_f32_32x32x16_bf16 v[48:63], v[120:123], v[88:91], v[48:63]
	v_mfma_f32_32x32x16_bf16 v[32:47], v[108:111], v[92:95], v[32:47]
	v_mfma_f32_32x32x16_bf16 v[48:63], v[124:127], v[92:95], v[48:63]
	v_add_u32_e32 v250, s100, v247
	ds_read_b64 v[64:65], v250 offset:8192
	ds_read_b64 v[66:67], v250 offset:8704
	ds_read_b64 v[68:69], v250 offset:9216
	ds_read_b64 v[70:71], v250 offset:9728
	ds_read_b64 v[72:73], v250 offset:10240
	ds_read_b64 v[74:75], v250 offset:10752
	ds_read_b64 v[76:77], v250 offset:11264
	ds_read_b64 v[78:79], v250 offset:11776
	ds_read_b64 v[172:173], v250 offset:12288
	ds_read_b64 v[174:175], v250 offset:12800
	ds_read_b64 v[176:177], v250 offset:13312
	ds_read_b64 v[178:179], v250 offset:13824
	ds_read_b64 v[180:181], v250 offset:14336
	ds_read_b64 v[182:183], v250 offset:14848
	ds_read_b64 v[184:185], v250 offset:15360
	ds_read_b64 v[186:187], v250 offset:15872
; #define NEGINF (-__builtin_inff())
; DI int crow(int i, int h) { return (i & 3) + 8 * (i >> 2) + 4 * h; }
; template <class KP, class VP, class ACT, class FILL>
; DI void attn_loop(AttnSt& st, const bf16x8 (&qf)[4], int k0, int k1, size_t vstride, KP kp, VP vp, ACT act, FILL fill) {
;     ...
;     if (act(kt)) {
;       float lg[16];
;       fill(kt, s_cur, lg);
;       softmax_step_r(st, lg, cur);
;     }
;     s_cur = s_next;
; #pragma unroll
;     for (int i = 0; i < 8; ++i) cur.v[i] = nxt.v[i];
; #pragma unroll
;     for (int ss = 0; ss < 4; ++ss) nxt.k[ss] = k2[ss];
;   }
; DI void nsa_main_item(const Params& p, int b, int head, int qb, const unsigned char* blut, const float* tbl) {
;     ...
;       [&](int kt, const f32x16& s, float (&lg)[16]) {
;         const bool bs = (selm >> (kt >> 1)) & 1ull;
;         if (qb * 32 - (kt * 32 + 31) >= 1513) {
;           const float b31 = tblh[31];
; #pragma unroll
;           for (int i = 0; i < 16; ++i) lg[i] = bs ? s[i] + b31 : NEGINF;
;         } else {
;           int dist[16]; float bv[16];
; #pragma unroll
;           for (int i = 0; i < 16; ++i) dist[i] = t - (kt * 32 + crow(i, h));
;           bias16(blut, tblh, dist, bv);
; #pragma unroll
;           for (int i = 0; i < 16; ++i) lg[i] = (bs && dist[i] >= 0) ? s[i] + bv[i] : NEGINF;
;         }
.Lasel_skipB2:
	s_add_u32 s100, s100, 0x4000
	s_cmp_eq_u32 s100, 0x1c000
	s_cselect_b32 s100, 0x10000, s100
	s_add_u32 s56, s56, 2
	s_cmp_le_u32 s56, s59
	s_cbranch_scc1 .Lasel_loopB
	s_sub_u32 s24, s56, 2
	s_cmp_le_u32 s24, s60
	s_cbranch_scc0 .Lasel_done
	s_sub_i32 s61, s60, s24
	s_lshr_b32 s23, s24, 1
	v_lshrrev_b64 v[248:249], s23, v[168:169]
	v_and_b32_e32 v248, 1, v248
	v_cmp_eq_u32_e64 s[62:63], 1, v248
	s_cmp_ge_i32 s61, 50
	s_cbranch_scc1 .Lasel_farc
	s_lshl_b32 s23, s61, 5
	v_add_u32_e32 v241, s23, v221
	v_lshl_add_u32 v244, v241, 2, v242
	v_subrev_u32_e32 v245, 128, v244
	ds_read_b32 v224, v244 offset:108
	ds_read_b32 v225, v244 offset:104
	ds_read_b32 v226, v244 offset:100
	ds_read_b32 v227, v244 offset:96
	ds_read_b32 v228, v244 offset:76
	ds_read_b32 v229, v244 offset:72
	ds_read_b32 v230, v244 offset:68
	ds_read_b32 v231, v244 offset:64
	ds_read_b32 v232, v244 offset:44
	ds_read_b32 v233, v244 offset:40
	ds_read_b32 v234, v244 offset:36
	ds_read_b32 v235, v244 offset:32
	ds_read_b32 v236, v244 offset:12
	ds_read_b32 v237, v244 offset:8
	ds_read_b32 v238, v244 offset:4
	ds_read_b32 v239, v244 offset:0
	s_waitcnt lgkmcnt(8)
	v_add_f32_e32 v32, v32, v224
	v_add_f32_e32 v33, v33, v225
	v_add_f32_e32 v34, v34, v226
	v_add_f32_e32 v35, v35, v227
	v_add_f32_e32 v36, v36, v228
	v_add_f32_e32 v37, v37, v229
	v_add_f32_e32 v38, v38, v230
	v_add_f32_e32 v39, v39, v231
	s_waitcnt lgkmcnt(0)
	v_add_f32_e32 v40, v40, v232
	v_add_f32_e32 v41, v41, v233
	v_add_f32_e32 v42, v42, v234
	v_add_f32_e32 v43, v43, v235
	v_add_f32_e32 v44, v44, v236
	v_add_f32_e32 v45, v45, v237
	v_add_f32_e32 v46, v46, v238
	v_add_f32_e32 v47, v47, v239
	ds_read_b32 v224, v245 offset:108
	ds_read_b32 v225, v245 offset:104
	ds_read_b32 v226, v245 offset:100
	ds_read_b32 v227, v245 offset:96
	ds_read_b32 v228, v245 offset:76
	ds_read_b32 v229, v245 offset:72
	ds_read_b32 v230, v245 offset:68
	ds_read_b32 v231, v245 offset:64
	ds_read_b32 v232, v245 offset:44
	ds_read_b32 v233, v245 offset:40
	ds_read_b32 v234, v245 offset:36
	ds_read_b32 v235, v245 offset:32
	ds_read_b32 v236, v245 offset:12
	ds_read_b32 v237, v245 offset:8
	ds_read_b32 v238, v245 offset:4
	ds_read_b32 v239, v245 offset:0
	s_waitcnt lgkmcnt(8)
	v_add_f32_e32 v48, v48, v224
	v_add_f32_e32 v49, v49, v225
	v_add_f32_e32 v50, v50, v226
	v_add_f32_e32 v51, v51, v227
	v_add_f32_e32 v52, v52, v228
	v_add_f32_e32 v53, v53, v229
	v_add_f32_e32 v54, v54, v230
	v_add_f32_e32 v55, v55, v231
	s_waitcnt lgkmcnt(0)
	v_add_f32_e32 v56, v56, v232
	v_add_f32_e32 v57, v57, v233
	v_add_f32_e32 v58, v58, v234
	v_add_f32_e32 v59, v59, v235
	v_add_f32_e32 v60, v60, v236
	v_add_f32_e32 v61, v61, v237
	v_add_f32_e32 v62, v62, v238
	v_add_f32_e32 v63, v63, v239
	s_cmp_ge_i32 s61, 2
	s_cbranch_scc1 .Lasel_softmaxc
	v_subrev_u32_e32 v246, 32, v241
	v_cmp_le_i32_e32 vcc, 0, v241
	s_nop 1
	v_cndmask_b32_e32 v32, v199, v32, vcc
	v_cmp_le_i32_e32 vcc, 1, v241
	s_nop 1
	v_cndmask_b32_e32 v33, v199, v33, vcc
	v_cmp_le_i32_e32 vcc, 2, v241
	s_nop 1
	v_cndmask_b32_e32 v34, v199, v34, vcc
	v_cmp_le_i32_e32 vcc, 3, v241
	s_nop 1
	v_cndmask_b32_e32 v35, v199, v35, vcc
	v_cmp_le_i32_e32 vcc, 8, v241
	s_nop 1
	v_cndmask_b32_e32 v36, v199, v36, vcc
	v_cmp_le_i32_e32 vcc, 9, v241
	s_nop 1
	v_cndmask_b32_e32 v37, v199, v37, vcc
	v_cmp_le_i32_e32 vcc, 10, v241
	s_nop 1
	v_cndmask_b32_e32 v38, v199, v38, vcc
	v_cmp_le_i32_e32 vcc, 11, v241
	s_nop 1
	v_cndmask_b32_e32 v39, v199, v39, vcc
	v_cmp_le_i32_e32 vcc, 16, v241
	s_nop 1
	v_cndmask_b32_e32 v40, v199, v40, vcc
	v_cmp_le_i32_e32 vcc, 17, v241
	s_nop 1
	v_cndmask_b32_e32 v41, v199, v41, vcc
	v_cmp_le_i32_e32 vcc, 18, v241
	s_nop 1
	v_cndmask_b32_e32 v42, v199, v42, vcc
	v_cmp_le_i32_e32 vcc, 19, v241
	s_nop 1
	v_cndmask_b32_e32 v43, v199, v43, vcc
	v_cmp_le_i32_e32 vcc, 24, v241
	s_nop 1
	v_cndmask_b32_e32 v44, v199, v44, vcc
	v_cmp_le_i32_e32 vcc, 25, v241
	s_nop 1
	v_cndmask_b32_e32 v45, v199, v45, vcc
	v_cmp_le_i32_e32 vcc, 26, v241
	s_nop 1
	v_cndmask_b32_e32 v46, v199, v46, vcc
	v_cmp_le_i32_e32 vcc, 27, v241
	s_nop 1
	v_cndmask_b32_e32 v47, v199, v47, vcc
	v_cmp_le_i32_e32 vcc, 0, v246
	s_nop 1
	v_cndmask_b32_e32 v48, v199, v48, vcc
	v_cmp_le_i32_e32 vcc, 1, v246
	s_nop 1
	v_cndmask_b32_e32 v49, v199, v49, vcc
	v_cmp_le_i32_e32 vcc, 2, v246
	s_nop 1
	v_cndmask_b32_e32 v50, v199, v50, vcc
	v_cmp_le_i32_e32 vcc, 3, v246
	s_nop 1
	v_cndmask_b32_e32 v51, v199, v51, vcc
	v_cmp_le_i32_e32 vcc, 8, v246
	s_nop 1
	v_cndmask_b32_e32 v52, v199, v52, vcc
	v_cmp_le_i32_e32 vcc, 9, v246
	s_nop 1
	v_cndmask_b32_e32 v53, v199, v53, vcc
	v_cmp_le_i32_e32 vcc, 10, v246
	s_nop 1
	v_cndmask_b32_e32 v54, v199, v54, vcc
	v_cmp_le_i32_e32 vcc, 11, v246
	s_nop 1
	v_cndmask_b32_e32 v55, v199, v55, vcc
	v_cmp_le_i32_e32 vcc, 16, v246
	s_nop 1
	v_cndmask_b32_e32 v56, v199, v56, vcc
	v_cmp_le_i32_e32 vcc, 17, v246
	s_nop 1
	v_cndmask_b32_e32 v57, v199, v57, vcc
	v_cmp_le_i32_e32 vcc, 18, v246
	s_nop 1
	v_cndmask_b32_e32 v58, v199, v58, vcc
	v_cmp_le_i32_e32 vcc, 19, v246
	s_nop 1
	v_cndmask_b32_e32 v59, v199, v59, vcc
	v_cmp_le_i32_e32 vcc, 24, v246
	s_nop 1
	v_cndmask_b32_e32 v60, v199, v60, vcc
	v_cmp_le_i32_e32 vcc, 25, v246
	s_nop 1
	v_cndmask_b32_e32 v61, v199, v61, vcc
	v_cmp_le_i32_e32 vcc, 26, v246
	s_nop 1
	v_cndmask_b32_e32 v62, v199, v62, vcc
	v_cmp_le_i32_e32 vcc, 27, v246
	s_nop 1
	v_cndmask_b32_e32 v63, v199, v63, vcc
	s_branch .Lasel_softmaxc

; #define MFMA32(a, b, c) __builtin_amdgcn_mfma_f32_32x32x16_bf16((a), (b), (c), 0, 0, 0)
; template <class KP, class VP, class ACT, class FILL>
; DI void attn_loop(AttnSt& st, const bf16x8 (&qf)[4], int k0, int k1, size_t vstride, KP kp, VP vp, ACT act, FILL fill) {
;     ...
;   for (int kt = k0; kt <= k1; ++kt) {
;     const int kn = (kt < k1) ? kt + 1 : k1;
;     const int kn2 = (kt + 2 <= k1) ? kt + 2 : k1;
;     {
;       const bf16_t* v0 = vp(kn);
; #pragma unroll
;       for (int j = 0; j < 8; ++j) nxt.v[j] = *(const s16x4*)(v0 + 256 * j);
;     }
;     bf16x8 k2[4];
;     {
;       const bf16_t* krow = kp(kn2);
; #pragma unroll
;       for (int ss = 0; ss < 4; ++ss) k2[ss] = *(const bf16x8*)(krow + 512 * ss);
;     }
;     f32x16 s_next;
; #pragma unroll
;     for (int i = 0; i < 16; ++i) s_next[i] = 0.f;
; #pragma unroll
;     for (int ss = 0; ss < 4; ++ss) s_next = MFMA32(nxt.k[ss], qf[ss], s_next);
;     if (act(kt)) {
;       float lg[16];
;       fill(kt, s_cur, lg);
;       softmax_step_r(st, lg, cur);
;     }
;     s_cur = s_next;
; #pragma unroll
;     for (int i = 0; i < 8; ++i) cur.v[i] = nxt.v[i];
; #pragma unroll
;     for (int ss = 0; ss < 4; ++ss) nxt.k[ss] = k2[ss];
;   }
; }
.Lasel_done:
	s_nop 15
	s_waitcnt vmcnt(0)
	s_mov_b64 s[58:59], 0
	s_branch .LBB0_701

; __global__ void __launch_bounds__(NTHREADS) mega_kernel(Params p) {
;     ...
;   for (int ph = 0; ph < NPHASE; ++ph) {
;     ...
;     const int nrep = (REPQ >= 100) ? ((ph == REPQ - 100) ? 2 : 1) : ((ph > 0 && ph < NPHASE - 1 && (ph - 1) % 14 == REPQ) ? 2 : 1);
;     ...
;     const int nrep = 1;
;     ...
;     if (ph == NPHASE - 2) continue;
;     for (int rep = 0; rep < nrep; ++rep) {
;       run_phase(p, ph, lds, rep);
;       if (ph + 1 < NPHASE) {
;         if (ph == 0) grid.sync();
;         else { ++bar_gen; grid_barrier((unsigned*)(p.ws + OFF_MISC + 6144), bar_gen * gridDim.x); }
;       }
;     }
;   }
.Ltramp_956:
	s_branch .LBB0_956
.Ltramp_914:
	s_branch .LBB0_914
